# final output stored without the non-temporal hint (the stores complete into the cache hierarchy instead of streaming to HBM at the end of the kernel)
# speedup vs baseline: 1.0057x; 1.0057x over previous
.Lot_epi_l1:
	s_waitcnt lgkmcnt(0)
	s_barrier
	ds_read_b128 v[0:3], v124 offset:0
	ds_read_b128 v[4:7], v124 offset:16
	ds_read_b128 v[8:11], v124 offset:8448
	ds_read_b128 v[12:15], v124 offset:8464
	ds_read_b128 v[16:19], v124 offset:16896
	ds_read_b128 v[20:23], v124 offset:16912
	ds_read_b128 v[24:27], v124 offset:25344
	ds_read_b128 v[28:31], v124 offset:25360
	ds_read_b128 v[32:35], v124 offset:33792
	ds_read_b128 v[36:39], v124 offset:33808
	ds_read_b128 v[40:43], v124 offset:42240
	ds_read_b128 v[44:47], v124 offset:42256
	ds_read_b128 v[48:51], v124 offset:50688
	ds_read_b128 v[52:55], v124 offset:50704
	ds_read_b128 v[56:59], v124 offset:59136
	ds_read_b128 v[60:63], v124 offset:59152
	s_waitcnt vmcnt(0)
	s_waitcnt lgkmcnt(14)
	v_lshlrev_b32_e32 v134, 16, v64
	v_fma_f32 v0, v208, v0, v134
	v_and_b32_e32 v136, 0xffff0000, v64
	v_fma_f32 v1, v209, v1, v136
	v_lshlrev_b32_e32 v134, 16, v65
	v_fma_f32 v2, v210, v2, v134
	v_and_b32_e32 v136, 0xffff0000, v65
	v_fma_f32 v3, v211, v3, v136
	v_lshlrev_b32_e32 v134, 16, v66
	v_fma_f32 v4, v212, v4, v134
	v_and_b32_e32 v136, 0xffff0000, v66
	v_fma_f32 v5, v213, v5, v136
	v_lshlrev_b32_e32 v134, 16, v67
	v_fma_f32 v6, v214, v6, v134
	v_and_b32_e32 v136, 0xffff0000, v67
	v_fma_f32 v7, v215, v7, v136
	v_add_u32_e32 v96, 0x0, v102
	global_store_dwordx4 v96, v[0:3], s[88:89]
	global_store_dwordx4 v96, v[4:7], s[88:89] offset:16
	s_waitcnt lgkmcnt(12)
	v_lshlrev_b32_e32 v134, 16, v68
	v_fma_f32 v8, v208, v8, v134
	v_and_b32_e32 v136, 0xffff0000, v68
	v_fma_f32 v9, v209, v9, v136
	v_lshlrev_b32_e32 v134, 16, v69
	v_fma_f32 v10, v210, v10, v134
	v_and_b32_e32 v136, 0xffff0000, v69
	v_fma_f32 v11, v211, v11, v136
	v_lshlrev_b32_e32 v134, 16, v70
	v_fma_f32 v12, v212, v12, v134
	v_and_b32_e32 v136, 0xffff0000, v70
	v_fma_f32 v13, v213, v13, v136
	v_lshlrev_b32_e32 v134, 16, v71
	v_fma_f32 v14, v214, v14, v134
	v_and_b32_e32 v136, 0xffff0000, v71
	v_fma_f32 v15, v215, v15, v136
	v_add_u32_e32 v96, 0x10000, v102
	global_store_dwordx4 v96, v[8:11], s[88:89]
	global_store_dwordx4 v96, v[12:15], s[88:89] offset:16
	s_waitcnt lgkmcnt(10)
	v_lshlrev_b32_e32 v134, 16, v192
	v_fma_f32 v16, v208, v16, v134
	v_and_b32_e32 v136, 0xffff0000, v192
	v_fma_f32 v17, v209, v17, v136
	v_lshlrev_b32_e32 v134, 16, v193
	v_fma_f32 v18, v210, v18, v134
	v_and_b32_e32 v136, 0xffff0000, v193
	v_fma_f32 v19, v211, v19, v136
	v_lshlrev_b32_e32 v134, 16, v194
	v_fma_f32 v20, v212, v20, v134
	v_and_b32_e32 v136, 0xffff0000, v194
	v_fma_f32 v21, v213, v21, v136
	v_lshlrev_b32_e32 v134, 16, v195
	v_fma_f32 v22, v214, v22, v134
	v_and_b32_e32 v136, 0xffff0000, v195
	v_fma_f32 v23, v215, v23, v136
	v_add_u32_e32 v96, 0x20000, v102
	global_store_dwordx4 v96, v[16:19], s[88:89]
	global_store_dwordx4 v96, v[20:23], s[88:89] offset:16
	s_waitcnt lgkmcnt(8)
	v_lshlrev_b32_e32 v134, 16, v196
	v_fma_f32 v24, v208, v24, v134
	v_and_b32_e32 v136, 0xffff0000, v196
	v_fma_f32 v25, v209, v25, v136
	v_lshlrev_b32_e32 v134, 16, v197
	v_fma_f32 v26, v210, v26, v134
	v_and_b32_e32 v136, 0xffff0000, v197
	v_fma_f32 v27, v211, v27, v136
	v_lshlrev_b32_e32 v134, 16, v198
	v_fma_f32 v28, v212, v28, v134
	v_and_b32_e32 v136, 0xffff0000, v198
	v_fma_f32 v29, v213, v29, v136
	v_lshlrev_b32_e32 v134, 16, v199
	v_fma_f32 v30, v214, v30, v134
	v_and_b32_e32 v136, 0xffff0000, v199
	v_fma_f32 v31, v215, v31, v136
	v_add_u32_e32 v96, 0x30000, v102
	global_store_dwordx4 v96, v[24:27], s[88:89]
	global_store_dwordx4 v96, v[28:31], s[88:89] offset:16
	s_waitcnt lgkmcnt(6)
	v_lshlrev_b32_e32 v134, 16, v200
	v_fma_f32 v32, v208, v32, v134
	v_and_b32_e32 v136, 0xffff0000, v200
	v_fma_f32 v33, v209, v33, v136
	v_lshlrev_b32_e32 v134, 16, v201
	v_fma_f32 v34, v210, v34, v134
	v_and_b32_e32 v136, 0xffff0000, v201
	v_fma_f32 v35, v211, v35, v136
	v_lshlrev_b32_e32 v134, 16, v202
	v_fma_f32 v36, v212, v36, v134
	v_and_b32_e32 v136, 0xffff0000, v202
	v_fma_f32 v37, v213, v37, v136
	v_lshlrev_b32_e32 v134, 16, v203
	v_fma_f32 v38, v214, v38, v134
	v_and_b32_e32 v136, 0xffff0000, v203
	v_fma_f32 v39, v215, v39, v136
	v_add_u32_e32 v96, 0x40000, v102
	global_store_dwordx4 v96, v[32:35], s[88:89]
	global_store_dwordx4 v96, v[36:39], s[88:89] offset:16
	s_waitcnt lgkmcnt(4)
	v_lshlrev_b32_e32 v134, 16, v110
	v_fma_f32 v40, v208, v40, v134
	v_and_b32_e32 v136, 0xffff0000, v110
	v_fma_f32 v41, v209, v41, v136
	v_lshlrev_b32_e32 v134, 16, v111
	v_fma_f32 v42, v210, v42, v134
	v_and_b32_e32 v136, 0xffff0000, v111
	v_fma_f32 v43, v211, v43, v136
	v_lshlrev_b32_e32 v134, 16, v112
	v_fma_f32 v44, v212, v44, v134
	v_and_b32_e32 v136, 0xffff0000, v112
	v_fma_f32 v45, v213, v45, v136
	v_lshlrev_b32_e32 v134, 16, v113
	v_fma_f32 v46, v214, v46, v134
	v_and_b32_e32 v136, 0xffff0000, v113
	v_fma_f32 v47, v215, v47, v136
	v_add_u32_e32 v96, 0x50000, v102
	global_store_dwordx4 v96, v[40:43], s[88:89]
	global_store_dwordx4 v96, v[44:47], s[88:89] offset:16
	s_waitcnt lgkmcnt(2)
	v_lshlrev_b32_e32 v134, 16, v116
	v_fma_f32 v48, v208, v48, v134
	v_and_b32_e32 v136, 0xffff0000, v116
	v_fma_f32 v49, v209, v49, v136
	v_lshlrev_b32_e32 v134, 16, v117
	v_fma_f32 v50, v210, v50, v134
	v_and_b32_e32 v136, 0xffff0000, v117
	v_fma_f32 v51, v211, v51, v136
	v_lshlrev_b32_e32 v134, 16, v118
	v_fma_f32 v52, v212, v52, v134
	v_and_b32_e32 v136, 0xffff0000, v118
	v_fma_f32 v53, v213, v53, v136
	v_lshlrev_b32_e32 v134, 16, v119
	v_fma_f32 v54, v214, v54, v134
	v_and_b32_e32 v136, 0xffff0000, v119
	v_fma_f32 v55, v215, v55, v136
	v_add_u32_e32 v96, 0x60000, v102
	global_store_dwordx4 v96, v[48:51], s[88:89]
	global_store_dwordx4 v96, v[52:55], s[88:89] offset:16
	s_waitcnt lgkmcnt(0)
	v_lshlrev_b32_e32 v134, 16, v120
	v_fma_f32 v56, v208, v56, v134
	v_and_b32_e32 v136, 0xffff0000, v120
	v_fma_f32 v57, v209, v57, v136
	v_lshlrev_b32_e32 v134, 16, v121
	v_fma_f32 v58, v210, v58, v134
	v_and_b32_e32 v136, 0xffff0000, v121
	v_fma_f32 v59, v211, v59, v136
	v_lshlrev_b32_e32 v134, 16, v122
	v_fma_f32 v60, v212, v60, v134
	v_and_b32_e32 v136, 0xffff0000, v122
	v_fma_f32 v61, v213, v61, v136
	v_lshlrev_b32_e32 v134, 16, v123
	v_fma_f32 v62, v214, v62, v134
	v_and_b32_e32 v136, 0xffff0000, v123
	v_fma_f32 v63, v215, v63, v136
	v_add_u32_e32 v96, 0x70000, v102
	global_store_dwordx4 v96, v[56:59], s[88:89]
	global_store_dwordx4 v96, v[60:63], s[88:89] offset:16
	s_branch .LBB0_624
